# v13 + nt hint on the sample-state stream LOADS only (stores plain) - split of v22 to see which half carries the gain
# speedup vs baseline: 1.0085x; 1.0003x over previous
; #define LAS __attribute__((address_space(3)))
; #define LAUNDER_PTR(p) do {} while (0)
; #define LAUNDER_PTR(p) asm volatile("" : "+v"(p))
; __device__ __forceinline__ void hgrn_sample_step(const bf16* proj, const float* lbs_l, const float* hgn_l, const float* state_in, float* state_out, bf16* ohg, int bh, int tid, LAS unsigned char* lds,
;                                                  f32x4 (&st)[8], int bh_next) {
;     ...
;     const int dv4 = tid & 31, rg = tid >> 5;
;     const f32x4 vv = *(const LAS f32x4*)(sv + 4 * dv4);
;     f32x4 oacc = (f32x4){0.f, 0.f, 0.f, 0.f};
;     float* op = state_out + (size_t)bh * 16384 + tid * 4;
;     const float* np = state_in + (size_t)(bh_next >= 0 ? bh_next : bh) * 16384 + tid * 4;
; #pragma unroll
;     for (int it = 0; it < 8; ++it) { const int dk = it * 16 + rg; const f32x4 sn = st[it] * sg[dk] + vv * sk[dk]; LAUNDER_PTR(op); *(f32x4*)op = sn; op += 2048; oacc = oacc + sn * sq[dk];
;         LAUNDER_PTR(np); if (bh_next >= 0) st[it] = *(const f32x4*)np; np += 2048; }
.LBB0_412:
	s_or_b64 exec, exec, s[8:9]
	v_lshlrev_b32_e32 v40, 2, v8
	v_and_b32_e32 v73, 0x7c, v40
	v_ashrrev_i32_e32 v71, 5, v8
	v_lshl_add_u32 v10, v73, 2, 0
	s_waitcnt lgkmcnt(0)
	s_barrier
	ds_read_b128 v[36:39], v10 offset:1536
	v_lshl_add_u32 v10, v71, 2, 0
	ds_read2st64_b32 v[42:43], v10 offset0:2 offset1:4
	s_add_i32 s19, s22, s90
	s_cmpk_gt_i32 s19, 0x3ff
	s_cselect_b64 s[12:13], -1, 0
	s_cmpk_lt_i32 s19, 0x400
	s_cselect_b32 s8, s19, -1
	v_ashrrev_i32_e32 v41, 31, v40
	v_lshlrev_b64 v[46:47], 2, v[40:41]
	s_cmp_gt_i32 s8, -1
	s_waitcnt lgkmcnt(0)
	v_mov_b32_e32 v40, v43
	s_cselect_b64 s[14:15], -1, 0
	v_pk_mul_f32 v[48:49], v[38:39], v[40:41] op_sel_hi:[1,0]
	v_pk_mul_f32 v[40:41], v[36:37], v[40:41] op_sel_hi:[1,0]
	v_lshl_add_u64 v[44:45], s[2:3], 0, v[46:47]
	s_and_b64 vcc, s[14:15], exec
	s_waitcnt vmcnt(0)
	v_pk_fma_f32 v[40:41], v[0:1], v[42:43], v[40:41] op_sel_hi:[1,0,1]
	v_pk_fma_f32 v[42:43], v[2:3], v[42:43], v[48:49] op_sel_hi:[1,0,1]
	s_cselect_b32 s8, s8, s22
	global_store_dwordx4 v[44:45], v[40:43], off
	s_ashr_i32 s9, s8, 31
	ds_read_b32 v70, v10
	s_lshl_b64 s[8:9], s[8:9], 16
	s_add_u32 s8, s16, s8
	s_addc_u32 s9, s17, s9
	v_lshl_add_u64 v[46:47], s[8:9], 0, v[46:47]
	s_cbranch_vccz .LBB0_414
	global_load_dwordx4 v[0:3], v[46:47], off nt
.LBB0_414:
	v_add_u32_e32 v66, 64, v10
	ds_read2st64_b32 v[50:51], v66 offset0:2 offset1:4
	v_lshl_add_u64 v[48:49], v[44:45], 0, s[44:45]
	v_lshl_add_u64 v[52:53], v[46:47], 0, s[44:45]
	s_andn2_b64 vcc, exec, s[14:15]
	s_waitcnt lgkmcnt(0)
	v_mov_b32_e32 v44, v51
	v_pk_mul_f32 v[46:47], v[38:39], v[44:45] op_sel_hi:[1,0]
	v_pk_mul_f32 v[44:45], v[36:37], v[44:45] op_sel_hi:[1,0]
	v_pk_fma_f32 v[46:47], v[6:7], v[50:51], v[46:47] op_sel_hi:[1,0,1]
	v_pk_fma_f32 v[44:45], v[4:5], v[50:51], v[44:45] op_sel_hi:[1,0,1]
	global_store_dwordx4 v[48:49], v[44:47], off
	ds_read_b32 v72, v10 offset:64
	v_cndmask_b32_e64 v50, 0, 1, s[14:15]
	v_cmp_ne_u32_e64 s[8:9], 1, v50
	s_cbranch_vccnz .LBB0_416
	global_load_dwordx4 v[4:7], v[52:53], off nt
.LBB0_416:
	v_add_u32_e32 v75, 0x80, v10
	ds_read2st64_b32 v[56:57], v75 offset0:2 offset1:4
	v_lshl_add_u64 v[54:55], v[48:49], 0, s[44:45]
	s_and_b64 vcc, exec, s[8:9]
	s_waitcnt lgkmcnt(0)
	v_mov_b32_e32 v48, v57
	v_pk_mul_f32 v[50:51], v[38:39], v[48:49] op_sel_hi:[1,0]
	v_pk_mul_f32 v[48:49], v[36:37], v[48:49] op_sel_hi:[1,0]
	v_pk_fma_f32 v[50:51], v[14:15], v[56:57], v[50:51] op_sel_hi:[1,0,1]
	v_pk_fma_f32 v[48:49], v[12:13], v[56:57], v[48:49] op_sel_hi:[1,0,1]
	global_store_dwordx4 v[54:55], v[48:51], off
	ds_read_b32 v74, v10 offset:128
	v_lshl_add_u64 v[56:57], v[52:53], 0, s[44:45]
	s_cbranch_vccnz .LBB0_418
	global_load_dwordx4 v[12:15], v[56:57], off nt
.LBB0_418:
	v_add_u32_e32 v77, 0xc0, v10
	ds_read2st64_b32 v[52:53], v77 offset0:2 offset1:4
	v_lshl_add_u64 v[58:59], v[54:55], 0, s[44:45]
	s_and_b64 vcc, exec, s[8:9]
	s_waitcnt lgkmcnt(0)
	v_mov_b32_e32 v54, v53
	v_pk_mul_f32 v[60:61], v[38:39], v[54:55] op_sel_hi:[1,0]
	v_pk_mul_f32 v[62:63], v[36:37], v[54:55] op_sel_hi:[1,0]
	v_pk_fma_f32 v[54:55], v[18:19], v[52:53], v[60:61] op_sel_hi:[1,0,1]
	v_pk_fma_f32 v[52:53], v[16:17], v[52:53], v[62:63] op_sel_hi:[1,0,1]
	global_store_dwordx4 v[58:59], v[52:55], off
	ds_read_b32 v76, v10 offset:192
	v_lshl_add_u64 v[60:61], v[56:57], 0, s[44:45]
	s_cbranch_vccnz .LBB0_420
	global_load_dwordx4 v[16:19], v[60:61], off nt
.LBB0_420:
	ds_read2st64_b32 v[56:57], v10 offset0:3 offset1:5
	v_lshl_add_u64 v[62:63], v[58:59], 0, s[44:45]
	s_and_b64 vcc, exec, s[8:9]
	s_waitcnt lgkmcnt(0)
	v_mov_b32_e32 v58, v57
	v_pk_mul_f32 v[64:65], v[38:39], v[58:59] op_sel_hi:[1,0]
	v_pk_mul_f32 v[78:79], v[36:37], v[58:59] op_sel_hi:[1,0]
	v_pk_fma_f32 v[58:59], v[22:23], v[56:57], v[64:65] op_sel_hi:[1,0,1]
	v_pk_fma_f32 v[56:57], v[20:21], v[56:57], v[78:79] op_sel_hi:[1,0,1]
	global_store_dwordx4 v[62:63], v[56:59], off
	ds_read_b32 v78, v10 offset:256
	v_lshl_add_u64 v[64:65], v[60:61], 0, s[44:45]
	s_cbranch_vccnz .LBB0_422
	global_load_dwordx4 v[20:23], v[64:65], off nt
.LBB0_422:
	ds_read2st64_b32 v[60:61], v66 offset0:3 offset1:5
	v_lshl_add_u64 v[66:67], v[62:63], 0, s[44:45]
	v_lshl_add_u64 v[84:85], v[64:65], 0, s[44:45]
	s_and_b64 vcc, exec, s[8:9]
	s_waitcnt lgkmcnt(0)
	v_mov_b32_e32 v62, v61
	v_pk_mul_f32 v[80:81], v[38:39], v[62:63] op_sel_hi:[1,0]
	v_pk_mul_f32 v[82:83], v[36:37], v[62:63] op_sel_hi:[1,0]
	v_pk_fma_f32 v[62:63], v[26:27], v[60:61], v[80:81] op_sel_hi:[1,0,1]
	v_pk_fma_f32 v[60:61], v[24:25], v[60:61], v[82:83] op_sel_hi:[1,0,1]
	global_store_dwordx4 v[66:67], v[60:63], off
	ds_read_b32 v80, v10 offset:320
	s_cbranch_vccnz .LBB0_424
	global_load_dwordx4 v[24:27], v[84:85], off nt
.LBB0_424:
	ds_read2st64_b32 v[64:65], v75 offset0:3 offset1:5
	v_lshl_add_u64 v[86:87], v[66:67], 0, s[44:45]
	s_and_b64 vcc, exec, s[8:9]
	s_waitcnt lgkmcnt(0)
	v_mov_b32_e32 v66, v65
	v_pk_mul_f32 v[82:83], v[38:39], v[66:67] op_sel_hi:[1,0]
	v_pk_mul_f32 v[88:89], v[36:37], v[66:67] op_sel_hi:[1,0]
	v_pk_fma_f32 v[66:67], v[30:31], v[64:65], v[82:83] op_sel_hi:[1,0,1]
	v_pk_fma_f32 v[64:65], v[28:29], v[64:65], v[88:89] op_sel_hi:[1,0,1]
	global_store_dwordx4 v[86:87], v[64:67], off
	ds_read_b32 v82, v10 offset:384
	v_lshl_add_u64 v[88:89], v[84:85], 0, s[44:45]
	s_cbranch_vccnz .LBB0_426
	global_load_dwordx4 v[28:31], v[88:89], off nt
.LBB0_426:
	ds_read2st64_b32 v[84:85], v77 offset0:3 offset1:5
	v_lshl_add_u64 v[86:87], v[86:87], 0, s[44:45]
	s_and_b64 vcc, exec, s[8:9]
	s_waitcnt lgkmcnt(0)
	v_mov_b32_e32 v90, v85
	v_pk_mul_f32 v[38:39], v[38:39], v[90:91] op_sel_hi:[1,0]
	v_pk_mul_f32 v[36:37], v[36:37], v[90:91] op_sel_hi:[1,0]
	v_pk_fma_f32 v[38:39], v[34:35], v[84:85], v[38:39] op_sel_hi:[1,0,1]
	v_pk_fma_f32 v[36:37], v[32:33], v[84:85], v[36:37] op_sel_hi:[1,0,1]
	global_store_dwordx4 v[86:87], v[36:39], off
	ds_read_b32 v84, v10 offset:448
	v_lshl_add_u64 v[86:87], v[88:89], 0, s[44:45]
	s_cbranch_vccnz .LBB0_428
	global_load_dwordx4 v[32:35], v[86:87], off nt

; #define LAS __attribute__((address_space(3)))
; #define LAUNDER_PTR(p) do {} while (0)
; #define LAUNDER_PTR(p) asm volatile("" : "+v"(p))
; __device__ __forceinline__ void ssd_sample_step(const bf16* proj, const float* conv_w, const float* conv_b, const float* dt_bias, const float* a_log, const float* d_skip, const float* ssm_norm, ...
;     ...
;     const int n4 = tid & 31, pr_ = tid >> 5;
;     const f32x4 Bv = *(const LAS f32x4*)(sB + 4 * n4), Cv = *(const LAS f32x4*)(sC + 4 * n4);
;     float* op = state_out + ((size_t)(b * 32 + grp * 4)) * 8192 + tid * 4;
;     const int bgn = bg_next >= 0 ? bg_next : bg; const float* np = state_in + ((size_t)((bgn >> 3) * 32 + (bgn & 7) * 4)) * 8192 + tid * 4;
; #pragma unroll
;     for (int it = 0; it < 16; ++it) { const int k = it >> 2, p = (it & 3) * 16 + pr_; const float xdt = sx[k * 64 + p] * sdt[k];
;         const f32x4 hn = st[it] * sdec[k] + Bv * xdt; LAUNDER_PTR(op); *(f32x4*)op = hn; op += 2048;
;         LAUNDER_PTR(np); if (bg_next >= 0) st[it] = *(const f32x4*)np; np += 2048;
.LBB0_461:
	s_or_b64 exec, exec, s[6:7]
	s_add_i32 s51, s59, s90
	s_cmpk_gt_i32 s51, 0x3ff
	s_cselect_b64 s[12:13], -1, 0
	s_cmpk_lt_i32 s51, 0x400
	s_cselect_b32 s8, s51, -1
	s_lshl_b32 s6, s58, 5
	s_lshl_b32 s58, s50, 2
	s_or_b32 s6, s6, s58
	s_ashr_i32 s7, s6, 31
	s_lshl_b64 s[6:7], s[6:7], 15
	s_add_u32 s6, s64, s6
	v_lshlrev_b32_e32 v72, 2, v8
	s_addc_u32 s7, s66, s7
	v_ashrrev_i32_e32 v73, 31, v72
	s_cmp_gt_i32 s8, -1
	v_lshlrev_b32_e32 v68, 4, v8
	v_lshlrev_b64 v[76:77], 2, v[72:73]
	s_cselect_b64 s[14:15], -1, 0
	v_ashrrev_i32_e32 v9, 5, v8
	v_and_b32_e32 v68, 0x1f0, v68
	v_lshl_add_u64 v[82:83], s[6:7], 0, v[76:77]
	s_and_b64 s[6:7], s[14:15], exec
	s_movk_i32 s9, 0x1000
	v_add_u32_e32 v74, 0, v68
	s_cselect_b32 s6, s8, s59
	v_lshl_add_u32 v81, v9, 2, 0
	v_add_u32_e64 v9, s9, 0
	s_waitcnt lgkmcnt(0)
	s_barrier
	ds_read_b128 v[68:71], v74 offset:3584
	s_lshl_b32 s6, s6, 2
	ds_read_b128 v[72:75], v74 offset:3072
	ds_read_b32 v86, v81 offset:2048
	ds_read2_b32 v[78:79], v9 offset1:4
	s_ashr_i32 s7, s6, 31
	s_lshl_b64 s[6:7], s[6:7], 15
	s_add_u32 s6, s20, s6
	s_addc_u32 s7, s21, s7
	v_lshl_add_u64 v[84:85], s[6:7], 0, v[76:77]
	s_waitcnt lgkmcnt(0)
	v_mov_b32_e32 v76, v79
	v_mul_f32_e32 v78, v86, v78
	v_pk_mul_f32 v[86:87], v[2:3], v[76:77] op_sel_hi:[1,0]
	v_pk_mul_f32 v[76:77], v[0:1], v[76:77] op_sel_hi:[1,0]
	s_cmp_lt_i32 s8, 0
	v_pk_fma_f32 v[76:77], v[72:73], v[78:79], v[76:77] op_sel_hi:[1,0,1]
	v_pk_fma_f32 v[78:79], v[74:75], v[78:79], v[86:87] op_sel_hi:[1,0,1]
	global_store_dwordx4 v[82:83], v[76:79], off
	s_cbranch_scc1 .LBB0_463
	global_load_dwordx4 v[0:3], v[84:85], off nt

; #define LAUNDER_PTR(p) do {} while (0)
; #define LAUNDER_PTR(p) asm volatile("" : "+v"(p))
; __device__ __forceinline__ void ssd_sample_step(const bf16* proj, const float* conv_w, const float* conv_b, const float* dt_bias, const float* a_log, const float* d_skip, const float* ssm_norm, ...
;     ...
;     for (int it = 0; it < 16; ++it) { const int k = it >> 2, p = (it & 3) * 16 + pr_; const float xdt = sx[k * 64 + p] * sdt[k];
;         const f32x4 hn = st[it] * sdec[k] + Bv * xdt; LAUNDER_PTR(op); *(f32x4*)op = hn; op += 2048;
;         LAUNDER_PTR(np); if (bg_next >= 0) st[it] = *(const f32x4*)np; np += 2048;
.LBB0_465:
	s_or_b64 exec, exec, s[8:9]
	ds_read_b32 v78, v81 offset:2112
	s_waitcnt lgkmcnt(0)
	ds_read2_b32 v[76:77], v9 offset1:4
	v_lshl_add_u64 v[84:85], v[84:85], 0, s[44:45]
	v_lshl_add_u64 v[82:83], v[82:83], 0, s[44:45]
	s_andn2_b64 vcc, exec, s[14:15]
	s_waitcnt lgkmcnt(0)
	v_mul_f32_e32 v76, v78, v76
	v_mov_b32_e32 v78, v77
	v_pk_mul_f32 v[86:87], v[6:7], v[78:79] op_sel_hi:[1,0]
	v_pk_mul_f32 v[88:89], v[4:5], v[78:79] op_sel_hi:[1,0]
	v_pk_fma_f32 v[78:79], v[74:75], v[76:77], v[86:87] op_sel_hi:[1,0,1]
	v_cndmask_b32_e64 v86, 0, 1, s[14:15]
	v_pk_fma_f32 v[76:77], v[72:73], v[76:77], v[88:89] op_sel_hi:[1,0,1]
	v_cmp_ne_u32_e64 s[8:9], 1, v86
	global_store_dwordx4 v[82:83], v[76:79], off
	s_cbranch_vccnz .LBB0_467
	global_load_dwordx4 v[4:7], v[84:85], off nt

; #define LAUNDER_PTR(p) do {} while (0)
; #define LAUNDER_PTR(p) asm volatile("" : "+v"(p))
; __device__ __forceinline__ void ssd_sample_step(const bf16* proj, const float* conv_w, const float* conv_b, const float* dt_bias, const float* a_log, const float* d_skip, const float* ssm_norm, ...
;     ...
;     for (int it = 0; it < 16; ++it) { const int k = it >> 2, p = (it & 3) * 16 + pr_; const float xdt = sx[k * 64 + p] * sdt[k];
;         const f32x4 hn = st[it] * sdec[k] + Bv * xdt; LAUNDER_PTR(op); *(f32x4*)op = hn; op += 2048;
;         LAUNDER_PTR(np); if (bg_next >= 0) st[it] = *(const f32x4*)np; np += 2048;
.LBB0_469:
	s_or_b64 exec, exec, s[14:15]
	ds_read_b32 v78, v81 offset:2176
	s_waitcnt lgkmcnt(0)
	ds_read2_b32 v[76:77], v9 offset1:4
	v_lshl_add_u64 v[84:85], v[84:85], 0, s[44:45]
	v_lshl_add_u64 v[82:83], v[82:83], 0, s[44:45]
	s_and_b64 vcc, exec, s[8:9]
	s_waitcnt lgkmcnt(0)
	v_mul_f32_e32 v76, v78, v76
	v_mov_b32_e32 v78, v77
	v_pk_mul_f32 v[86:87], v[14:15], v[78:79] op_sel_hi:[1,0]
	v_pk_mul_f32 v[88:89], v[12:13], v[78:79] op_sel_hi:[1,0]
	v_pk_fma_f32 v[78:79], v[74:75], v[76:77], v[86:87] op_sel_hi:[1,0,1]
	v_pk_fma_f32 v[76:77], v[72:73], v[76:77], v[88:89] op_sel_hi:[1,0,1]
	global_store_dwordx4 v[82:83], v[76:79], off
	s_cbranch_vccnz .LBB0_471
	global_load_dwordx4 v[12:15], v[84:85], off nt

; #define LAUNDER_PTR(p) do {} while (0)
; #define LAUNDER_PTR(p) asm volatile("" : "+v"(p))
; __device__ __forceinline__ void ssd_sample_step(const bf16* proj, const float* conv_w, const float* conv_b, const float* dt_bias, const float* a_log, const float* d_skip, const float* ssm_norm, ...
;     ...
;     for (int it = 0; it < 16; ++it) { const int k = it >> 2, p = (it & 3) * 16 + pr_; const float xdt = sx[k * 64 + p] * sdt[k];
;         const f32x4 hn = st[it] * sdec[k] + Bv * xdt; LAUNDER_PTR(op); *(f32x4*)op = hn; op += 2048;
;         LAUNDER_PTR(np); if (bg_next >= 0) st[it] = *(const f32x4*)np; np += 2048;
.LBB0_473:
	s_or_b64 exec, exec, s[14:15]
	ds_read_b32 v78, v81 offset:2240
	s_waitcnt lgkmcnt(0)
	ds_read2_b32 v[76:77], v9 offset1:4
	v_lshl_add_u64 v[84:85], v[84:85], 0, s[44:45]
	v_lshl_add_u64 v[82:83], v[82:83], 0, s[44:45]
	s_and_b64 vcc, exec, s[8:9]
	s_waitcnt lgkmcnt(0)
	v_mul_f32_e32 v76, v78, v76
	v_mov_b32_e32 v78, v77
	v_pk_mul_f32 v[86:87], v[18:19], v[78:79] op_sel_hi:[1,0]
	v_pk_mul_f32 v[88:89], v[16:17], v[78:79] op_sel_hi:[1,0]
	v_pk_fma_f32 v[78:79], v[74:75], v[76:77], v[86:87] op_sel_hi:[1,0,1]
	v_pk_fma_f32 v[76:77], v[72:73], v[76:77], v[88:89] op_sel_hi:[1,0,1]
	global_store_dwordx4 v[82:83], v[76:79], off
	s_cbranch_vccnz .LBB0_475
	global_load_dwordx4 v[16:19], v[84:85], off nt

; #define LAUNDER_PTR(p) do {} while (0)
; #define LAUNDER_PTR(p) asm volatile("" : "+v"(p))
; __device__ __forceinline__ void ssd_sample_step(const bf16* proj, const float* conv_w, const float* conv_b, const float* dt_bias, const float* a_log, const float* d_skip, const float* ssm_norm, ...
;     ...
;     for (int it = 0; it < 16; ++it) { const int k = it >> 2, p = (it & 3) * 16 + pr_; const float xdt = sx[k * 64 + p] * sdt[k];
;         const f32x4 hn = st[it] * sdec[k] + Bv * xdt; LAUNDER_PTR(op); *(f32x4*)op = hn; op += 2048;
;         LAUNDER_PTR(np); if (bg_next >= 0) st[it] = *(const f32x4*)np; np += 2048;
.LBB0_477:
	s_or_b64 exec, exec, s[14:15]
	ds_read_b32 v78, v81 offset:2304
	s_waitcnt lgkmcnt(0)
	ds_read2_b32 v[76:77], v9 offset0:1 offset1:5
	v_lshl_add_u64 v[84:85], v[84:85], 0, s[44:45]
	v_lshl_add_u64 v[82:83], v[82:83], 0, s[44:45]
	s_and_b64 vcc, exec, s[8:9]
	s_waitcnt lgkmcnt(0)
	v_mul_f32_e32 v76, v78, v76
	v_mov_b32_e32 v78, v77
	v_pk_mul_f32 v[86:87], v[22:23], v[78:79] op_sel_hi:[1,0]
	v_pk_mul_f32 v[88:89], v[20:21], v[78:79] op_sel_hi:[1,0]
	v_pk_fma_f32 v[78:79], v[74:75], v[76:77], v[86:87] op_sel_hi:[1,0,1]
	v_pk_fma_f32 v[76:77], v[72:73], v[76:77], v[88:89] op_sel_hi:[1,0,1]
	global_store_dwordx4 v[82:83], v[76:79], off
	s_cbranch_vccnz .LBB0_479
	global_load_dwordx4 v[20:23], v[84:85], off nt

; #define LAUNDER_PTR(p) do {} while (0)
; #define LAUNDER_PTR(p) asm volatile("" : "+v"(p))
; __device__ __forceinline__ void ssd_sample_step(const bf16* proj, const float* conv_w, const float* conv_b, const float* dt_bias, const float* a_log, const float* d_skip, const float* ssm_norm, ...
;     ...
;     for (int it = 0; it < 16; ++it) { const int k = it >> 2, p = (it & 3) * 16 + pr_; const float xdt = sx[k * 64 + p] * sdt[k];
;         const f32x4 hn = st[it] * sdec[k] + Bv * xdt; LAUNDER_PTR(op); *(f32x4*)op = hn; op += 2048;
;         LAUNDER_PTR(np); if (bg_next >= 0) st[it] = *(const f32x4*)np; np += 2048;
.LBB0_481:
	s_or_b64 exec, exec, s[14:15]
	ds_read_b32 v78, v81 offset:2368
	s_waitcnt lgkmcnt(0)
	ds_read2_b32 v[76:77], v9 offset0:1 offset1:5
	v_lshl_add_u64 v[84:85], v[84:85], 0, s[44:45]
	v_lshl_add_u64 v[82:83], v[82:83], 0, s[44:45]
	s_and_b64 vcc, exec, s[8:9]
	s_waitcnt lgkmcnt(0)
	v_mul_f32_e32 v76, v78, v76
	v_mov_b32_e32 v78, v77
	v_pk_mul_f32 v[86:87], v[26:27], v[78:79] op_sel_hi:[1,0]
	v_pk_mul_f32 v[88:89], v[24:25], v[78:79] op_sel_hi:[1,0]
	v_pk_fma_f32 v[78:79], v[74:75], v[76:77], v[86:87] op_sel_hi:[1,0,1]
	v_pk_fma_f32 v[76:77], v[72:73], v[76:77], v[88:89] op_sel_hi:[1,0,1]
	global_store_dwordx4 v[82:83], v[76:79], off
	s_cbranch_vccnz .LBB0_483
	global_load_dwordx4 v[24:27], v[84:85], off nt

; #define LAUNDER_PTR(p) do {} while (0)
; #define LAUNDER_PTR(p) asm volatile("" : "+v"(p))
; __device__ __forceinline__ void ssd_sample_step(const bf16* proj, const float* conv_w, const float* conv_b, const float* dt_bias, const float* a_log, const float* d_skip, const float* ssm_norm, ...
;     ...
;     for (int it = 0; it < 16; ++it) { const int k = it >> 2, p = (it & 3) * 16 + pr_; const float xdt = sx[k * 64 + p] * sdt[k];
;         const f32x4 hn = st[it] * sdec[k] + Bv * xdt; LAUNDER_PTR(op); *(f32x4*)op = hn; op += 2048;
;         LAUNDER_PTR(np); if (bg_next >= 0) st[it] = *(const f32x4*)np; np += 2048;
.LBB0_485:
	s_or_b64 exec, exec, s[14:15]
	ds_read_b32 v78, v81 offset:2432
	s_waitcnt lgkmcnt(0)
	ds_read2_b32 v[76:77], v9 offset0:1 offset1:5
	v_lshl_add_u64 v[84:85], v[84:85], 0, s[44:45]
	v_lshl_add_u64 v[82:83], v[82:83], 0, s[44:45]
	s_and_b64 vcc, exec, s[8:9]
	s_waitcnt lgkmcnt(0)
	v_mul_f32_e32 v76, v78, v76
	v_mov_b32_e32 v78, v77
	v_pk_mul_f32 v[86:87], v[30:31], v[78:79] op_sel_hi:[1,0]
	v_pk_mul_f32 v[88:89], v[28:29], v[78:79] op_sel_hi:[1,0]
	v_pk_fma_f32 v[78:79], v[74:75], v[76:77], v[86:87] op_sel_hi:[1,0,1]
	v_pk_fma_f32 v[76:77], v[72:73], v[76:77], v[88:89] op_sel_hi:[1,0,1]
	global_store_dwordx4 v[82:83], v[76:79], off
	s_cbranch_vccnz .LBB0_487
	global_load_dwordx4 v[28:31], v[84:85], off nt

; #define LAUNDER_PTR(p) do {} while (0)
; #define LAUNDER_PTR(p) asm volatile("" : "+v"(p))
; __device__ __forceinline__ void ssd_sample_step(const bf16* proj, const float* conv_w, const float* conv_b, const float* dt_bias, const float* a_log, const float* d_skip, const float* ssm_norm, ...
;     ...
;     for (int it = 0; it < 16; ++it) { const int k = it >> 2, p = (it & 3) * 16 + pr_; const float xdt = sx[k * 64 + p] * sdt[k];
;         const f32x4 hn = st[it] * sdec[k] + Bv * xdt; LAUNDER_PTR(op); *(f32x4*)op = hn; op += 2048;
;         LAUNDER_PTR(np); if (bg_next >= 0) st[it] = *(const f32x4*)np; np += 2048;
.LBB0_489:
	s_or_b64 exec, exec, s[14:15]
	ds_read_b32 v78, v81 offset:2496
	s_waitcnt lgkmcnt(0)
	ds_read2_b32 v[76:77], v9 offset0:1 offset1:5
	v_lshl_add_u64 v[84:85], v[84:85], 0, s[44:45]
	v_lshl_add_u64 v[82:83], v[82:83], 0, s[44:45]
	s_and_b64 vcc, exec, s[8:9]
	s_waitcnt lgkmcnt(0)
	v_mul_f32_e32 v76, v78, v76
	v_mov_b32_e32 v78, v77
	v_pk_mul_f32 v[86:87], v[34:35], v[78:79] op_sel_hi:[1,0]
	v_pk_mul_f32 v[88:89], v[32:33], v[78:79] op_sel_hi:[1,0]
	v_pk_fma_f32 v[78:79], v[74:75], v[76:77], v[86:87] op_sel_hi:[1,0,1]
	v_pk_fma_f32 v[76:77], v[72:73], v[76:77], v[88:89] op_sel_hi:[1,0,1]
	global_store_dwordx4 v[82:83], v[76:79], off
	s_cbranch_vccnz .LBB0_491
	global_load_dwordx4 v[32:35], v[84:85], off nt

; #define LAUNDER_PTR(p) do {} while (0)
; #define LAUNDER_PTR(p) asm volatile("" : "+v"(p))
; __device__ __forceinline__ void ssd_sample_step(const bf16* proj, const float* conv_w, const float* conv_b, const float* dt_bias, const float* a_log, const float* d_skip, const float* ssm_norm, ...
;     ...
;     for (int it = 0; it < 16; ++it) { const int k = it >> 2, p = (it & 3) * 16 + pr_; const float xdt = sx[k * 64 + p] * sdt[k];
;         const f32x4 hn = st[it] * sdec[k] + Bv * xdt; LAUNDER_PTR(op); *(f32x4*)op = hn; op += 2048;
;         LAUNDER_PTR(np); if (bg_next >= 0) st[it] = *(const f32x4*)np; np += 2048;
.LBB0_493:
	s_or_b64 exec, exec, s[14:15]
	ds_read_b32 v78, v81 offset:2560
	s_waitcnt lgkmcnt(0)
	ds_read2_b32 v[76:77], v9 offset0:2 offset1:6
	v_lshl_add_u64 v[84:85], v[84:85], 0, s[44:45]
	v_lshl_add_u64 v[82:83], v[82:83], 0, s[44:45]
	s_and_b64 vcc, exec, s[8:9]
	s_waitcnt lgkmcnt(0)
	v_mul_f32_e32 v76, v78, v76
	v_mov_b32_e32 v78, v77
	v_pk_mul_f32 v[86:87], v[38:39], v[78:79] op_sel_hi:[1,0]
	v_pk_mul_f32 v[88:89], v[36:37], v[78:79] op_sel_hi:[1,0]
	v_pk_fma_f32 v[78:79], v[74:75], v[76:77], v[86:87] op_sel_hi:[1,0,1]
	v_pk_fma_f32 v[76:77], v[72:73], v[76:77], v[88:89] op_sel_hi:[1,0,1]
	global_store_dwordx4 v[82:83], v[76:79], off
	s_cbranch_vccnz .LBB0_495
	global_load_dwordx4 v[36:39], v[84:85], off nt

; #define LAUNDER_PTR(p) do {} while (0)
; #define LAUNDER_PTR(p) asm volatile("" : "+v"(p))
; __device__ __forceinline__ void ssd_sample_step(const bf16* proj, const float* conv_w, const float* conv_b, const float* dt_bias, const float* a_log, const float* d_skip, const float* ssm_norm, ...
;     ...
;     for (int it = 0; it < 16; ++it) { const int k = it >> 2, p = (it & 3) * 16 + pr_; const float xdt = sx[k * 64 + p] * sdt[k];
;         const f32x4 hn = st[it] * sdec[k] + Bv * xdt; LAUNDER_PTR(op); *(f32x4*)op = hn; op += 2048;
;         LAUNDER_PTR(np); if (bg_next >= 0) st[it] = *(const f32x4*)np; np += 2048;
.LBB0_497:
	s_or_b64 exec, exec, s[14:15]
	ds_read_b32 v78, v81 offset:2624
	s_waitcnt lgkmcnt(0)
	ds_read2_b32 v[76:77], v9 offset0:2 offset1:6
	v_lshl_add_u64 v[84:85], v[84:85], 0, s[44:45]
	v_lshl_add_u64 v[82:83], v[82:83], 0, s[44:45]
	s_and_b64 vcc, exec, s[8:9]
	s_waitcnt lgkmcnt(0)
	v_mul_f32_e32 v76, v78, v76
	v_mov_b32_e32 v78, v77
	v_pk_mul_f32 v[86:87], v[42:43], v[78:79] op_sel_hi:[1,0]
	v_pk_mul_f32 v[88:89], v[40:41], v[78:79] op_sel_hi:[1,0]
	v_pk_fma_f32 v[78:79], v[74:75], v[76:77], v[86:87] op_sel_hi:[1,0,1]
	v_pk_fma_f32 v[76:77], v[72:73], v[76:77], v[88:89] op_sel_hi:[1,0,1]
	global_store_dwordx4 v[82:83], v[76:79], off
	s_cbranch_vccnz .LBB0_499
	global_load_dwordx4 v[40:43], v[84:85], off nt

; #define LAUNDER_PTR(p) do {} while (0)
; #define LAUNDER_PTR(p) asm volatile("" : "+v"(p))
; __device__ __forceinline__ void ssd_sample_step(const bf16* proj, const float* conv_w, const float* conv_b, const float* dt_bias, const float* a_log, const float* d_skip, const float* ssm_norm, ...
;     ...
;     for (int it = 0; it < 16; ++it) { const int k = it >> 2, p = (it & 3) * 16 + pr_; const float xdt = sx[k * 64 + p] * sdt[k];
;         const f32x4 hn = st[it] * sdec[k] + Bv * xdt; LAUNDER_PTR(op); *(f32x4*)op = hn; op += 2048;
;         LAUNDER_PTR(np); if (bg_next >= 0) st[it] = *(const f32x4*)np; np += 2048;
.LBB0_501:
	s_or_b64 exec, exec, s[14:15]
	ds_read_b32 v78, v81 offset:2688
	s_waitcnt lgkmcnt(0)
	ds_read2_b32 v[76:77], v9 offset0:2 offset1:6
	v_lshl_add_u64 v[84:85], v[84:85], 0, s[44:45]
	v_lshl_add_u64 v[82:83], v[82:83], 0, s[44:45]
	s_and_b64 vcc, exec, s[8:9]
	s_waitcnt lgkmcnt(0)
	v_mul_f32_e32 v76, v78, v76
	v_mov_b32_e32 v78, v77
	v_pk_mul_f32 v[86:87], v[46:47], v[78:79] op_sel_hi:[1,0]
	v_pk_mul_f32 v[88:89], v[44:45], v[78:79] op_sel_hi:[1,0]
	v_pk_fma_f32 v[78:79], v[74:75], v[76:77], v[86:87] op_sel_hi:[1,0,1]
	v_pk_fma_f32 v[76:77], v[72:73], v[76:77], v[88:89] op_sel_hi:[1,0,1]
	global_store_dwordx4 v[82:83], v[76:79], off
	s_cbranch_vccnz .LBB0_503
	global_load_dwordx4 v[44:47], v[84:85], off nt

; #define LAUNDER_PTR(p) do {} while (0)
; #define LAUNDER_PTR(p) asm volatile("" : "+v"(p))
; __device__ __forceinline__ void ssd_sample_step(const bf16* proj, const float* conv_w, const float* conv_b, const float* dt_bias, const float* a_log, const float* d_skip, const float* ssm_norm, ...
;     ...
;     for (int it = 0; it < 16; ++it) { const int k = it >> 2, p = (it & 3) * 16 + pr_; const float xdt = sx[k * 64 + p] * sdt[k];
;         const f32x4 hn = st[it] * sdec[k] + Bv * xdt; LAUNDER_PTR(op); *(f32x4*)op = hn; op += 2048;
;         LAUNDER_PTR(np); if (bg_next >= 0) st[it] = *(const f32x4*)np; np += 2048;
.LBB0_505:
	s_or_b64 exec, exec, s[14:15]
	ds_read_b32 v78, v81 offset:2752
	s_waitcnt lgkmcnt(0)
	ds_read2_b32 v[76:77], v9 offset0:2 offset1:6
	v_lshl_add_u64 v[84:85], v[84:85], 0, s[44:45]
	v_lshl_add_u64 v[82:83], v[82:83], 0, s[44:45]
	s_and_b64 vcc, exec, s[8:9]
	s_waitcnt lgkmcnt(0)
	v_mul_f32_e32 v76, v78, v76
	v_mov_b32_e32 v78, v77
	v_pk_mul_f32 v[86:87], v[50:51], v[78:79] op_sel_hi:[1,0]
	v_pk_mul_f32 v[88:89], v[48:49], v[78:79] op_sel_hi:[1,0]
	v_pk_fma_f32 v[78:79], v[74:75], v[76:77], v[86:87] op_sel_hi:[1,0,1]
	v_pk_fma_f32 v[76:77], v[72:73], v[76:77], v[88:89] op_sel_hi:[1,0,1]
	global_store_dwordx4 v[82:83], v[76:79], off
	s_cbranch_vccnz .LBB0_507
	global_load_dwordx4 v[48:51], v[84:85], off nt

; #define LAUNDER_PTR(p) do {} while (0)
; #define LAUNDER_PTR(p) asm volatile("" : "+v"(p))
; __device__ __forceinline__ void ssd_sample_step(const bf16* proj, const float* conv_w, const float* conv_b, const float* dt_bias, const float* a_log, const float* d_skip, const float* ssm_norm, ...
;     ...
;     for (int it = 0; it < 16; ++it) { const int k = it >> 2, p = (it & 3) * 16 + pr_; const float xdt = sx[k * 64 + p] * sdt[k];
;         const f32x4 hn = st[it] * sdec[k] + Bv * xdt; LAUNDER_PTR(op); *(f32x4*)op = hn; op += 2048;
;         LAUNDER_PTR(np); if (bg_next >= 0) st[it] = *(const f32x4*)np; np += 2048;
.LBB0_509:
	s_or_b64 exec, exec, s[14:15]
	ds_read_b32 v78, v81 offset:2816
	s_waitcnt lgkmcnt(0)
	ds_read2_b32 v[76:77], v9 offset0:3 offset1:7
	v_lshl_add_u64 v[84:85], v[84:85], 0, s[44:45]
	v_lshl_add_u64 v[82:83], v[82:83], 0, s[44:45]
	s_and_b64 vcc, exec, s[8:9]
	s_waitcnt lgkmcnt(0)
	v_mul_f32_e32 v76, v78, v76
	v_mov_b32_e32 v78, v77
	v_pk_mul_f32 v[86:87], v[54:55], v[78:79] op_sel_hi:[1,0]
	v_pk_mul_f32 v[88:89], v[52:53], v[78:79] op_sel_hi:[1,0]
	v_pk_fma_f32 v[78:79], v[74:75], v[76:77], v[86:87] op_sel_hi:[1,0,1]
	v_pk_fma_f32 v[76:77], v[72:73], v[76:77], v[88:89] op_sel_hi:[1,0,1]
	global_store_dwordx4 v[82:83], v[76:79], off
	s_cbranch_vccnz .LBB0_511
	global_load_dwordx4 v[52:55], v[84:85], off nt

; #define LAUNDER_PTR(p) do {} while (0)
; #define LAUNDER_PTR(p) asm volatile("" : "+v"(p))
; __device__ __forceinline__ void ssd_sample_step(const bf16* proj, const float* conv_w, const float* conv_b, const float* dt_bias, const float* a_log, const float* d_skip, const float* ssm_norm, ...
;     ...
;     for (int it = 0; it < 16; ++it) { const int k = it >> 2, p = (it & 3) * 16 + pr_; const float xdt = sx[k * 64 + p] * sdt[k];
;         const f32x4 hn = st[it] * sdec[k] + Bv * xdt; LAUNDER_PTR(op); *(f32x4*)op = hn; op += 2048;
;         LAUNDER_PTR(np); if (bg_next >= 0) st[it] = *(const f32x4*)np; np += 2048;
.LBB0_513:
	s_or_b64 exec, exec, s[14:15]
	ds_read_b32 v78, v81 offset:2880
	s_waitcnt lgkmcnt(0)
	ds_read2_b32 v[76:77], v9 offset0:3 offset1:7
	v_lshl_add_u64 v[84:85], v[84:85], 0, s[44:45]
	v_lshl_add_u64 v[82:83], v[82:83], 0, s[44:45]
	s_and_b64 vcc, exec, s[8:9]
	s_waitcnt lgkmcnt(0)
	v_mul_f32_e32 v76, v78, v76
	v_mov_b32_e32 v78, v77
	v_pk_mul_f32 v[86:87], v[58:59], v[78:79] op_sel_hi:[1,0]
	v_pk_mul_f32 v[88:89], v[56:57], v[78:79] op_sel_hi:[1,0]
	v_pk_fma_f32 v[78:79], v[74:75], v[76:77], v[86:87] op_sel_hi:[1,0,1]
	v_pk_fma_f32 v[76:77], v[72:73], v[76:77], v[88:89] op_sel_hi:[1,0,1]
	global_store_dwordx4 v[82:83], v[76:79], off
	s_cbranch_vccnz .LBB0_515
	global_load_dwordx4 v[56:59], v[84:85], off nt

; #define LAUNDER_PTR(p) do {} while (0)
; #define LAUNDER_PTR(p) asm volatile("" : "+v"(p))
; __device__ __forceinline__ void ssd_sample_step(const bf16* proj, const float* conv_w, const float* conv_b, const float* dt_bias, const float* a_log, const float* d_skip, const float* ssm_norm, ...
;     ...
;     for (int it = 0; it < 16; ++it) { const int k = it >> 2, p = (it & 3) * 16 + pr_; const float xdt = sx[k * 64 + p] * sdt[k];
;         const f32x4 hn = st[it] * sdec[k] + Bv * xdt; LAUNDER_PTR(op); *(f32x4*)op = hn; op += 2048;
;         LAUNDER_PTR(np); if (bg_next >= 0) st[it] = *(const f32x4*)np; np += 2048;
.LBB0_517:
	s_or_b64 exec, exec, s[14:15]
	ds_read_b32 v78, v81 offset:2944
	s_waitcnt lgkmcnt(0)
	ds_read2_b32 v[76:77], v9 offset0:3 offset1:7
	v_lshl_add_u64 v[84:85], v[84:85], 0, s[44:45]
	v_lshl_add_u64 v[82:83], v[82:83], 0, s[44:45]
	s_and_b64 vcc, exec, s[8:9]
	s_waitcnt lgkmcnt(0)
	v_mul_f32_e32 v76, v78, v76
	v_mov_b32_e32 v78, v77
	v_pk_mul_f32 v[86:87], v[62:63], v[78:79] op_sel_hi:[1,0]
	v_pk_mul_f32 v[88:89], v[60:61], v[78:79] op_sel_hi:[1,0]
	v_pk_fma_f32 v[78:79], v[74:75], v[76:77], v[86:87] op_sel_hi:[1,0,1]
	v_pk_fma_f32 v[76:77], v[72:73], v[76:77], v[88:89] op_sel_hi:[1,0,1]
	global_store_dwordx4 v[82:83], v[76:79], off
	s_cbranch_vccnz .LBB0_519
	global_load_dwordx4 v[60:63], v[84:85], off nt

; #define LAUNDER_PTR(p) do {} while (0)
; #define LAUNDER_PTR(p) asm volatile("" : "+v"(p))
; __device__ __forceinline__ void ssd_sample_step(const bf16* proj, const float* conv_w, const float* conv_b, const float* dt_bias, const float* a_log, const float* d_skip, const float* ssm_norm, ...
;     ...
;     for (int it = 0; it < 16; ++it) { const int k = it >> 2, p = (it & 3) * 16 + pr_; const float xdt = sx[k * 64 + p] * sdt[k];
;         const f32x4 hn = st[it] * sdec[k] + Bv * xdt; LAUNDER_PTR(op); *(f32x4*)op = hn; op += 2048;
;         LAUNDER_PTR(np); if (bg_next >= 0) st[it] = *(const f32x4*)np; np += 2048;
.LBB0_521:
	s_or_b64 exec, exec, s[14:15]
	ds_read_b32 v86, v81 offset:3008
	ds_read2_b32 v[78:79], v9 offset0:3 offset1:7
	s_waitcnt lgkmcnt(0)
	v_lshl_add_u64 v[76:77], v[84:85], 0, s[44:45]
	v_lshl_add_u64 v[82:83], v[82:83], 0, s[44:45]
	s_and_b64 vcc, exec, s[8:9]
	v_mov_b32_e32 v84, v79
	v_mul_f32_e32 v78, v86, v78
	v_pk_mul_f32 v[86:87], v[66:67], v[84:85] op_sel_hi:[1,0]
	v_pk_mul_f32 v[84:85], v[64:65], v[84:85] op_sel_hi:[1,0]
	v_pk_fma_f32 v[74:75], v[74:75], v[78:79], v[86:87] op_sel_hi:[1,0,1]
	v_pk_fma_f32 v[72:73], v[72:73], v[78:79], v[84:85] op_sel_hi:[1,0,1]
	global_store_dwordx4 v[82:83], v[72:75], off
	s_cbranch_vccnz .LBB0_523
	global_load_dwordx4 v[64:67], v[76:77], off nt

; #define LAS __attribute__((address_space(3)))
; #define LAUNDER_PTR(p) do {} while (0)
; #define LAUNDER_PTR(p) asm volatile("" : "+v"(p))
; __device__ __forceinline__ void hgrn_sample_step(const bf16* proj, const float* lbs_l, const float* hgn_l, const float* state_in, float* state_out, bf16* ohg, int bh, int tid, LAS unsigned char* lds,
;                                                  f32x4 (&st)[8], int bh_next) {
;     ...
;     const int dv4 = tid & 31, rg = tid >> 5;
;     const f32x4 vv = *(const LAS f32x4*)(sv + 4 * dv4);
;     f32x4 oacc = (f32x4){0.f, 0.f, 0.f, 0.f};
;     float* op = state_out + (size_t)bh * 16384 + tid * 4;
;     const float* np = state_in + (size_t)(bh_next >= 0 ? bh_next : bh) * 16384 + tid * 4;
; #pragma unroll
;     for (int it = 0; it < 8; ++it) { const int dk = it * 16 + rg; const f32x4 sn = st[it] * sg[dk] + vv * sk[dk]; LAUNDER_PTR(op); *(f32x4*)op = sn; op += 2048; oacc = oacc + sn * sq[dk];
;         LAUNDER_PTR(np); if (bh_next >= 0) st[it] = *(const f32x4*)np; np += 2048; }
.LBB0_556:
	s_or_b64 exec, exec, s[8:9]
	v_lshlrev_b32_e32 v40, 2, v8
	v_and_b32_e32 v73, 0x7c, v40
	v_ashrrev_i32_e32 v71, 5, v8
	v_lshl_add_u32 v10, v73, 2, 0
	s_waitcnt lgkmcnt(0)
	s_barrier
	ds_read_b128 v[36:39], v10 offset:1536
	v_lshl_add_u32 v10, v71, 2, 0
	ds_read2st64_b32 v[42:43], v10 offset0:2 offset1:4
	s_add_i32 s17, s18, s90
	s_cmpk_gt_i32 s17, 0x3ff
	s_cselect_b64 s[12:13], -1, 0
	s_cmpk_lt_i32 s17, 0x400
	s_cselect_b32 s8, s17, -1
	v_ashrrev_i32_e32 v41, 31, v40
	v_lshlrev_b64 v[46:47], 2, v[40:41]
	s_cmp_gt_i32 s8, -1
	s_waitcnt lgkmcnt(0)
	v_mov_b32_e32 v40, v43
	s_cselect_b64 s[14:15], -1, 0
	v_pk_mul_f32 v[48:49], v[38:39], v[40:41] op_sel_hi:[1,0]
	v_pk_mul_f32 v[40:41], v[36:37], v[40:41] op_sel_hi:[1,0]
	v_lshl_add_u64 v[44:45], s[2:3], 0, v[46:47]
	s_and_b64 vcc, s[14:15], exec
	v_pk_fma_f32 v[40:41], v[0:1], v[42:43], v[40:41] op_sel_hi:[1,0,1]
	v_pk_fma_f32 v[42:43], v[2:3], v[42:43], v[48:49] op_sel_hi:[1,0,1]
	s_cselect_b32 s8, s8, s18
	global_store_dwordx4 v[44:45], v[40:43], off
	s_ashr_i32 s9, s8, 31
	ds_read_b32 v70, v10
	s_lshl_b64 s[8:9], s[8:9], 16
	s_add_u32 s8, s0, s8
	s_addc_u32 s9, s1, s9
	v_lshl_add_u64 v[46:47], s[8:9], 0, v[46:47]
	s_cbranch_vccz .LBB0_558
	global_load_dwordx4 v[0:3], v[46:47], off nt

; #define LAS __attribute__((address_space(3)))
; #define LAUNDER_PTR(p) do {} while (0)
; #define LAUNDER_PTR(p) asm volatile("" : "+v"(p))
; __device__ __forceinline__ void ssd_sample_step(const bf16* proj, const float* conv_w, const float* conv_b, const float* dt_bias, const float* a_log, const float* d_skip, const float* ssm_norm, ...
;     ...
;     const int n4 = tid & 31, pr_ = tid >> 5;
;     const f32x4 Bv = *(const LAS f32x4*)(sB + 4 * n4), Cv = *(const LAS f32x4*)(sC + 4 * n4);
;     float* op = state_out + ((size_t)(b * 32 + grp * 4)) * 8192 + tid * 4;
;     const int bgn = bg_next >= 0 ? bg_next : bg; const float* np = state_in + ((size_t)((bgn >> 3) * 32 + (bgn & 7) * 4)) * 8192 + tid * 4;
; #pragma unroll
;     for (int it = 0; it < 16; ++it) { const int k = it >> 2, p = (it & 3) * 16 + pr_; const float xdt = sx[k * 64 + p] * sdt[k];
;         const f32x4 hn = st[it] * sdec[k] + Bv * xdt; LAUNDER_PTR(op); *(f32x4*)op = hn; op += 2048;
;         LAUNDER_PTR(np); if (bg_next >= 0) st[it] = *(const f32x4*)np; np += 2048;
.LBB0_605:
	s_or_b64 exec, exec, s[6:7]
	s_add_i32 s29, s51, s90
	s_cmpk_gt_i32 s29, 0x3ff
	s_cselect_b64 s[12:13], -1, 0
	s_cmpk_lt_i32 s29, 0x400
	s_cselect_b32 s8, s29, -1
	s_lshl_b32 s6, s50, 5
	s_lshl_b32 s50, s28, 2
	s_or_b32 s6, s6, s50
	s_ashr_i32 s7, s6, 31
	s_lshl_b64 s[6:7], s[6:7], 15
	s_add_u32 s6, s20, s6
	v_lshlrev_b32_e32 v72, 2, v8
	s_addc_u32 s7, s21, s7
	v_ashrrev_i32_e32 v73, 31, v72
	s_cmp_gt_i32 s8, -1
	v_lshlrev_b32_e32 v68, 4, v8
	v_lshlrev_b64 v[76:77], 2, v[72:73]
	s_cselect_b64 s[14:15], -1, 0
	v_ashrrev_i32_e32 v9, 5, v8
	v_and_b32_e32 v68, 0x1f0, v68
	v_lshl_add_u64 v[82:83], s[6:7], 0, v[76:77]
	s_and_b64 s[6:7], s[14:15], exec
	s_movk_i32 s9, 0x1000
	v_add_u32_e32 v74, 0, v68
	s_cselect_b32 s6, s8, s51
	v_lshl_add_u32 v81, v9, 2, 0
	v_add_u32_e64 v9, s9, 0
	s_waitcnt lgkmcnt(0)
	s_barrier
	ds_read_b128 v[68:71], v74 offset:3584
	s_lshl_b32 s6, s6, 2
	ds_read_b128 v[72:75], v74 offset:3072
	ds_read_b32 v86, v81 offset:2048
	ds_read2_b32 v[78:79], v9 offset1:4
	s_ashr_i32 s7, s6, 31
	s_lshl_b64 s[6:7], s[6:7], 15
	s_add_u32 s6, s0, s6
	s_addc_u32 s7, s1, s7
	v_lshl_add_u64 v[84:85], s[6:7], 0, v[76:77]
	s_waitcnt lgkmcnt(0)
	v_mov_b32_e32 v76, v79
	v_mul_f32_e32 v78, v86, v78
	v_pk_mul_f32 v[86:87], v[2:3], v[76:77] op_sel_hi:[1,0]
	v_pk_mul_f32 v[76:77], v[0:1], v[76:77] op_sel_hi:[1,0]
	s_cmp_lt_i32 s8, 0
	v_pk_fma_f32 v[76:77], v[72:73], v[78:79], v[76:77] op_sel_hi:[1,0,1]
	v_pk_fma_f32 v[78:79], v[74:75], v[78:79], v[86:87] op_sel_hi:[1,0,1]
	global_store_dwordx4 v[82:83], v[76:79], off
	s_cbranch_scc1 .LBB0_607
	global_load_dwordx4 v[0:3], v[84:85], off nt
